# KV-cache conversion filler: nt (streaming) hint on its read-once f32 loads and its bf16 stores so they do not displace the GEMM operands in cache
# speedup vs baseline: 1.0189x; 1.0059x over previous
.LBB0_134:
	s_mov_b32 s4, 0xffffc300
	s_cmp_eq_u32 s75, 3
	s_cselect_b32 s4, 0xffffd980, s4
	v_mov_b32_e32 v120, 0xfffff600
	v_mov_b32_e32 v121, s4
	v_cmp_gt_i32_e32 vcc, s97, v11
	s_nop 0
	v_cndmask_b32_e32 v120, v120, v121, vcc
	v_add_u32_e32 v120, v120, v11
	s_movk_i32 s4, 0xdeff
	v_cmp_lt_i32_e32 vcc, s4, v120
	s_and_saveexec_b64 s[4:5], vcc
	s_xor_b64 s[40:41], exec, s[4:5]
	s_cbranch_execz .LBB0_170
	v_subrev_co_u32_e32 v0, vcc, 0xffffdf00, v120
	s_movk_i32 s4, 0xdeff
	s_mov_b64 s[38:39], vcc
	v_cmp_lt_u32_e32 vcc, s4, v120
	s_movk_i32 s4, 0x1080
	s_nop 0
	v_cndmask_b32_e32 v0, v120, v0, vcc
	v_add_u32_e32 v2, 0xef80, v0
	v_cmp_gt_u32_e32 vcc, s4, v0
	s_mov_b32 s4, 0xf83f
	s_nop 0
	v_cndmask_b32_e32 v3, v2, v0, vcc
	v_mul_u32_u24_sdwa v2, v3, s4 dst_sel:DWORD dst_unused:UNUSED_PAD src0_sel:WORD_0 src1_sel:DWORD
	v_lshrrev_b32_e32 v2, 25, v2
	v_mul_lo_u16_e32 v4, 0x210, v2
	v_sub_u16_e32 v3, v3, v4
	v_and_b32_e32 v4, 0x3fc, v3
	s_movk_i32 s4, 0x200
	v_cmp_ne_u32_e32 vcc, s4, v4
	s_and_saveexec_b64 s[42:43], vcc
	s_cbranch_execz .LBB0_169
	s_movk_i32 s4, 0x107f
	v_cmp_lt_u32_e32 vcc, s4, v0
	v_and_b32_e32 v20, 0xffff, v2
	s_movk_i32 s4, 0x200
	v_cndmask_b32_e64 v21, 0, 1, vcc
	v_lshlrev_b32_e32 v0, 3, v21
	global_load_dwordx2 v[18:19], v0, s[0:1] offset:32
	v_cndmask_b32_e64 v0, 0, 8, s[38:39]
	v_add_lshl_u32 v0, v0, v20, 23
	v_mov_b32_e32 v2, 0
	v_cmp_gt_u16_e32 vcc, s4, v3
	v_lshlrev_b32_e32 v8, 4, v10
	v_mov_b32_e32 v4, 0
	v_mov_b32_e32 v5, 0
	v_mov_b32_e32 v6, 0
	v_mov_b32_e32 v7, 0
	s_waitcnt vmcnt(0)
	v_lshl_add_u64 v[18:19], v[18:19], 0, v[0:1]
	v_lshlrev_b32_e32 v0, 14, v3
	v_lshl_add_u64 v[24:25], v[18:19], 0, v[0:1]
	s_and_saveexec_b64 s[48:49], vcc
	s_cbranch_execz .LBB0_138
	v_mov_b32_e32 v9, v1
	v_lshl_add_u64 v[4:5], v[24:25], 0, v[8:9]
	global_load_dwordx4 v[4:7], v[4:5], off nt

.Lkvba_ld:
	s_and_saveexec_b64 s[98:99], vcc
	v_mov_b32_e32 v9, v1
	v_lshl_add_u64 v[110:111], v[24:25], 0, v[8:9]
	s_mov_b64 s[100:101], 0x1000
	v_lshl_add_u64 v[112:113], v[110:111], 0, s[100:101]
	v_lshl_add_u64 v[114:115], v[112:113], 0, s[100:101]
	v_lshl_add_u64 v[116:117], v[114:115], 0, s[100:101]
	global_load_dwordx4 v[50:53], v[110:111], off offset:1024 nt
	global_load_dwordx4 v[54:57], v[110:111], off offset:2048 nt
	global_load_dwordx4 v[58:61], v[110:111], off offset:3072 nt
	global_load_dwordx4 v[62:65], v[112:113], off nt
	global_load_dwordx4 v[66:69], v[112:113], off offset:1024 nt
	global_load_dwordx4 v[70:73], v[112:113], off offset:2048 nt
	global_load_dwordx4 v[74:77], v[112:113], off offset:3072 nt
	global_load_dwordx4 v[78:81], v[114:115], off nt
	global_load_dwordx4 v[82:85], v[114:115], off offset:1024 nt
	global_load_dwordx4 v[86:89], v[114:115], off offset:2048 nt
	global_load_dwordx4 v[90:93], v[114:115], off offset:3072 nt
	global_load_dwordx4 v[94:97], v[116:117], off nt
	global_load_dwordx4 v[98:101], v[116:117], off offset:1024 nt
	global_load_dwordx4 v[102:105], v[116:117], off offset:2048 nt
	global_load_dwordx4 v[106:109], v[116:117], off offset:3072 nt
	s_or_b64 exec, exec, s[98:99]
	s_load_dwordx2 s[4:5], s[0:1], 0xd0
	v_cndmask_b32_e64 v0, 0, 2, s[38:39]
	v_or_b32_e32 v0, v0, v21
	s_mov_b32 s8, 0x2100000
	v_mul_lo_u32 v0, v0, s8
	s_waitcnt lgkmcnt(0)
	v_lshl_add_u64 v[22:23], s[4:5], 0, v[0:1]
	v_mul_u32_u24_e32 v0, 0x210000, v20
	v_lshlrev_b32_e32 v0, 1, v0
	v_lshlrev_b32_e32 v36, 12, v3
	v_lshl_add_u64 v[20:21], v[22:23], 0, v[0:1]
	s_mov_b64 s[4:5], 0x9200000
	v_lshl_add_u64 v[20:21], v[20:21], 0, s[4:5]
	v_lshlrev_b32_e32 v0, 1, v36
	v_lshl_add_u64 v[22:23], v[20:21], 0, v[0:1]
	s_waitcnt vmcnt(0)
	v_bfe_u32 v0, v4, 16, 1
	v_add3_u32 v0, v4, v0, s91
	v_bfe_u32 v3, v5, 16, 1
	v_lshrrev_b32_e32 v0, 16, v0
	v_add3_u32 v3, v5, v3, s91
	v_and_or_b32 v4, v3, s92, v0
	v_bfe_u32 v0, v6, 16, 1
	v_add3_u32 v0, v6, v0, s91
	v_bfe_u32 v3, v7, 16, 1
	v_lshrrev_b32_e32 v0, 16, v0
	v_add3_u32 v3, v7, v3, s91
	v_and_or_b32 v5, v3, s92, v0
	v_lshlrev_b32_e32 v0, 3, v10
	v_lshl_add_u64 v[22:23], v[22:23], 0, v[0:1]
	global_store_dwordx2 v[22:23], v[4:5], off nt
	s_mov_b64 s[100:101], 0x1000
	v_lshl_add_u64 v[118:119], v[22:23], 0, s[100:101]
	v_cvt_pk_bf16_f32 v50, v50, v51
	v_cvt_pk_bf16_f32 v51, v52, v53
	global_store_dwordx2 v[22:23], v[50:51], off offset:512 nt
	v_cvt_pk_bf16_f32 v54, v54, v55
	v_cvt_pk_bf16_f32 v55, v56, v57
	global_store_dwordx2 v[22:23], v[54:55], off offset:1024 nt
	v_cvt_pk_bf16_f32 v58, v58, v59
	v_cvt_pk_bf16_f32 v59, v60, v61
	global_store_dwordx2 v[22:23], v[58:59], off offset:1536 nt
	v_cvt_pk_bf16_f32 v62, v62, v63
	v_cvt_pk_bf16_f32 v63, v64, v65
	global_store_dwordx2 v[22:23], v[62:63], off offset:2048 nt
	v_cvt_pk_bf16_f32 v66, v66, v67
	v_cvt_pk_bf16_f32 v67, v68, v69
	global_store_dwordx2 v[22:23], v[66:67], off offset:2560 nt
	v_cvt_pk_bf16_f32 v70, v70, v71
	v_cvt_pk_bf16_f32 v71, v72, v73
	global_store_dwordx2 v[22:23], v[70:71], off offset:3072 nt
	v_cvt_pk_bf16_f32 v74, v74, v75
	v_cvt_pk_bf16_f32 v75, v76, v77
	global_store_dwordx2 v[22:23], v[74:75], off offset:3584 nt
	v_cvt_pk_bf16_f32 v78, v78, v79
	v_cvt_pk_bf16_f32 v79, v80, v81
	global_store_dwordx2 v[118:119], v[78:79], off nt
	v_cvt_pk_bf16_f32 v82, v82, v83
	v_cvt_pk_bf16_f32 v83, v84, v85
	global_store_dwordx2 v[118:119], v[82:83], off offset:512 nt
	v_cvt_pk_bf16_f32 v86, v86, v87
	v_cvt_pk_bf16_f32 v87, v88, v89
	global_store_dwordx2 v[118:119], v[86:87], off offset:1024 nt
	v_cvt_pk_bf16_f32 v90, v90, v91
	v_cvt_pk_bf16_f32 v91, v92, v93
	global_store_dwordx2 v[118:119], v[90:91], off offset:1536 nt
	v_cvt_pk_bf16_f32 v94, v94, v95
	v_cvt_pk_bf16_f32 v95, v96, v97
	global_store_dwordx2 v[118:119], v[94:95], off offset:2048 nt
	v_cvt_pk_bf16_f32 v98, v98, v99
	v_cvt_pk_bf16_f32 v99, v100, v101
	global_store_dwordx2 v[118:119], v[98:99], off offset:2560 nt
	v_cvt_pk_bf16_f32 v102, v102, v103
	v_cvt_pk_bf16_f32 v103, v104, v105
	global_store_dwordx2 v[118:119], v[102:103], off offset:3072 nt
	v_cvt_pk_bf16_f32 v106, v106, v107
	v_cvt_pk_bf16_f32 v107, v108, v109
	global_store_dwordx2 v[118:119], v[106:107], off offset:3584 nt

.LBB0_259:
	s_movk_i32 s4, 0xa00
	v_cmp_gt_i32_e32 vcc, s4, v11
	s_movk_i32 s4, 0x4dff
	s_nop 0
	v_cndmask_b32_e32 v0, v215, v216, vcc
	v_add_u32_e32 v0, v0, v11
	v_cmp_lt_i32_e32 vcc, s4, v0
	s_and_saveexec_b64 s[4:5], vcc
	s_xor_b64 s[42:43], exec, s[4:5]
	s_cbranch_execz .LBB0_295
	v_add_u32_e32 v2, 0xffffb200, v0
	s_movk_i32 s4, 0x1080
	v_add_u32_e32 v0, 0xa180, v0
	v_cmp_gt_u32_e32 vcc, s4, v2
	s_mov_b32 s4, 0xf83f
	s_nop 0
	v_cndmask_b32_e32 v0, v0, v2, vcc
	v_mul_u32_u24_sdwa v3, v0, s4 dst_sel:DWORD dst_unused:UNUSED_PAD src0_sel:WORD_0 src1_sel:DWORD
	v_lshrrev_b32_e32 v3, 25, v3
	v_mul_lo_u16_e32 v4, 0x210, v3
	v_sub_u16_e32 v20, v0, v4
	v_and_b32_e32 v0, 0x3fc, v20
	s_movk_i32 s4, 0x200
	v_cmp_ne_u32_e32 vcc, s4, v0
	s_and_saveexec_b64 s[48:49], vcc
	s_cbranch_execz .LBB0_294
	s_movk_i32 s4, 0x107f
	v_cmp_lt_u32_e64 s[40:41], s4, v2
	s_movk_i32 s4, 0x200
	v_cmp_gt_u16_e32 vcc, s4, v20
	v_cndmask_b32_e64 v0, 0, 1, s[40:41]
	v_lshlrev_b32_e32 v0, 3, v0
	global_load_dwordx2 v[18:19], v0, s[0:1] offset:32
	v_lshlrev_b32_e32 v0, 23, v3
	v_mov_b32_e32 v2, 0
	v_lshlrev_b32_e32 v8, 4, v10
	v_mov_b32_e32 v4, 0
	v_mov_b32_e32 v5, 0
	v_mov_b32_e32 v6, 0
	v_mov_b32_e32 v7, 0
	s_waitcnt vmcnt(0)
	v_lshl_add_u64 v[18:19], v[18:19], 0, v[0:1]
	v_lshlrev_b32_e32 v0, 14, v20
	v_lshl_add_u64 v[24:25], v[18:19], 0, v[0:1]
	s_and_saveexec_b64 s[50:51], vcc
	s_cbranch_execz .LBB0_263
	v_mov_b32_e32 v9, v1
	v_lshl_add_u64 v[4:5], v[24:25], 0, v[8:9]
	global_load_dwordx4 v[4:7], v[4:5], off nt

.Lkvbb_ld:
	s_and_saveexec_b64 s[98:99], vcc
	v_mov_b32_e32 v9, v1
	v_lshl_add_u64 v[110:111], v[24:25], 0, v[8:9]
	s_mov_b64 s[100:101], 0x1000
	v_lshl_add_u64 v[112:113], v[110:111], 0, s[100:101]
	v_lshl_add_u64 v[114:115], v[112:113], 0, s[100:101]
	v_lshl_add_u64 v[116:117], v[114:115], 0, s[100:101]
	global_load_dwordx4 v[50:53], v[110:111], off offset:1024 nt
	global_load_dwordx4 v[54:57], v[110:111], off offset:2048 nt
	global_load_dwordx4 v[58:61], v[110:111], off offset:3072 nt
	global_load_dwordx4 v[62:65], v[112:113], off nt
	global_load_dwordx4 v[66:69], v[112:113], off offset:1024 nt
	global_load_dwordx4 v[70:73], v[112:113], off offset:2048 nt
	global_load_dwordx4 v[74:77], v[112:113], off offset:3072 nt
	global_load_dwordx4 v[78:81], v[114:115], off nt
	global_load_dwordx4 v[82:85], v[114:115], off offset:1024 nt
	global_load_dwordx4 v[86:89], v[114:115], off offset:2048 nt
	global_load_dwordx4 v[90:93], v[114:115], off offset:3072 nt
	global_load_dwordx4 v[94:97], v[116:117], off nt
	global_load_dwordx4 v[98:101], v[116:117], off offset:1024 nt
	global_load_dwordx4 v[102:105], v[116:117], off offset:2048 nt
	global_load_dwordx4 v[106:109], v[116:117], off offset:3072 nt
	s_or_b64 exec, exec, s[98:99]
	s_load_dwordx2 s[4:5], s[0:1], 0xd0
	v_cndmask_b32_e64 v0, 0, v217, s[40:41]
	v_and_b32_e32 v3, 0xffff, v3
	v_lshlrev_b32_e32 v36, 12, v20
	s_waitcnt lgkmcnt(0)
	v_lshl_add_u64 v[20:21], s[4:5], 0, v[0:1]
	s_mov_b32 s4, 0x420000
	v_mad_u64_u32 v[20:21], s[4:5], v3, s4, v[20:21]
	s_mov_b64 s[4:5], 0x9200000
	s_nop 0
	v_lshl_add_u64 v[20:21], v[20:21], 0, s[4:5]
	v_lshlrev_b32_e32 v0, 1, v36
	v_lshl_add_u64 v[22:23], v[20:21], 0, v[0:1]
	s_waitcnt vmcnt(0)
	v_bfe_u32 v0, v4, 16, 1
	v_add3_u32 v0, v4, v0, s91
	v_bfe_u32 v3, v5, 16, 1
	v_lshrrev_b32_e32 v0, 16, v0
	v_add3_u32 v3, v5, v3, s91
	v_and_or_b32 v4, v3, s92, v0
	v_bfe_u32 v0, v6, 16, 1
	v_add3_u32 v0, v6, v0, s91
	v_bfe_u32 v3, v7, 16, 1
	v_lshrrev_b32_e32 v0, 16, v0
	v_add3_u32 v3, v7, v3, s91
	v_and_or_b32 v5, v3, s92, v0
	v_lshlrev_b32_e32 v0, 3, v10
	v_lshl_add_u64 v[22:23], v[22:23], 0, v[0:1]
	global_store_dwordx2 v[22:23], v[4:5], off nt
	s_mov_b64 s[100:101], 0x1000
	v_lshl_add_u64 v[118:119], v[22:23], 0, s[100:101]
	v_cvt_pk_bf16_f32 v50, v50, v51
	v_cvt_pk_bf16_f32 v51, v52, v53
	global_store_dwordx2 v[22:23], v[50:51], off offset:512 nt
	v_cvt_pk_bf16_f32 v54, v54, v55
	v_cvt_pk_bf16_f32 v55, v56, v57
	global_store_dwordx2 v[22:23], v[54:55], off offset:1024 nt
	v_cvt_pk_bf16_f32 v58, v58, v59
	v_cvt_pk_bf16_f32 v59, v60, v61
	global_store_dwordx2 v[22:23], v[58:59], off offset:1536 nt
	v_cvt_pk_bf16_f32 v62, v62, v63
	v_cvt_pk_bf16_f32 v63, v64, v65
	global_store_dwordx2 v[22:23], v[62:63], off offset:2048 nt
	v_cvt_pk_bf16_f32 v66, v66, v67
	v_cvt_pk_bf16_f32 v67, v68, v69
	global_store_dwordx2 v[22:23], v[66:67], off offset:2560 nt
	v_cvt_pk_bf16_f32 v70, v70, v71
	v_cvt_pk_bf16_f32 v71, v72, v73
	global_store_dwordx2 v[22:23], v[70:71], off offset:3072 nt
	v_cvt_pk_bf16_f32 v74, v74, v75
	v_cvt_pk_bf16_f32 v75, v76, v77
	global_store_dwordx2 v[22:23], v[74:75], off offset:3584 nt
	v_cvt_pk_bf16_f32 v78, v78, v79
	v_cvt_pk_bf16_f32 v79, v80, v81
	global_store_dwordx2 v[118:119], v[78:79], off nt
	v_cvt_pk_bf16_f32 v82, v82, v83
	v_cvt_pk_bf16_f32 v83, v84, v85
	global_store_dwordx2 v[118:119], v[82:83], off offset:512 nt
	v_cvt_pk_bf16_f32 v86, v86, v87
	v_cvt_pk_bf16_f32 v87, v88, v89
	global_store_dwordx2 v[118:119], v[86:87], off offset:1024 nt
	v_cvt_pk_bf16_f32 v90, v90, v91
	v_cvt_pk_bf16_f32 v91, v92, v93
	global_store_dwordx2 v[118:119], v[90:91], off offset:1536 nt
	v_cvt_pk_bf16_f32 v94, v94, v95
	v_cvt_pk_bf16_f32 v95, v96, v97
	global_store_dwordx2 v[118:119], v[94:95], off offset:2048 nt
	v_cvt_pk_bf16_f32 v98, v98, v99
	v_cvt_pk_bf16_f32 v99, v100, v101
	global_store_dwordx2 v[118:119], v[98:99], off offset:2560 nt
	v_cvt_pk_bf16_f32 v102, v102, v103
	v_cvt_pk_bf16_f32 v103, v104, v105
	global_store_dwordx2 v[118:119], v[102:103], off offset:3072 nt
	v_cvt_pk_bf16_f32 v106, v106, v107
	v_cvt_pk_bf16_f32 v107, v108, v109
	global_store_dwordx2 v[118:119], v[106:107], off offset:3584 nt
